# P2a: next unit's Q rows requested at the top of the last tile (one tile more lead); last tile's V wait counts the 8 younger loads
# speedup vs baseline: 1.0124x; 1.0011x over previous
; #define GAS __attribute__((address_space(1)))
; __device__ __forceinline__ void at_load_q(bf16x8 (&qr)[8], const bf16_t* qb, int tq0, int dil, int lane) {
;     const bf16_t* qrow = qb + (size_t)(tq0 + dil * (lane & 31)) * 128 + (lane >> 5) * 8;
; #pragma unroll
;     for (int s = 0; s < 8; ++s) qr[s] = *(const GAS bf16x8*)(qrow + 16 * s);
; __device__ __forceinline__ void attn_unit(const bool FINAL, const bool HN, LAS unsigned char* wl, const bf16_t* qb, const bf16_t* kb, const bf16_t* vb, int tq0, int dil, float sl, bf16x8 (&qr)[8], const bf16_t* nqb, const bf16_t* nkb, const bf16_t* nvb, int ntq0, int ndil, ...
;     ...
; #pragma unroll
;         for (int s = 0; s < 8; ++s) p = __builtin_amdgcn_mfma_f32_32x32x16_fp8_fp8(kf[s], q8[s], p, 0, 0, 0);
;         const float relb = (float)(32 * n + 4 * hi - 64 - r32) - 8.0f;
;     ...
;         float tmax = -1e30f;
;         if (interior && n == 2) {
; #pragma unroll
;             for (int r = 0; r < 16; ++r) { const float rel = relb + AT_CR(r); p[r] = p[r] - sl * fabsf(rel); tmax = fmaxf(tmax, p[r]); }
;         } else if (interior) {
;             const float ssl = (n < 2) ? sl : -sl;
;             if (n == 0) {
; #pragma unroll
;                 for (int r = 0; r < 16; ++r) { const float rel = relb + AT_CR(r); const float v = __builtin_fmaf(ssl, rel, p[r]); p[r] = (rel >= -64.f) ? v : -1e30f; tmax = fmaxf(tmax, p[r]); }
;             } else if (n == 4) {
; #pragma unroll
;                 for (int r = 0; r < 16; ++r) { const float rel = relb + AT_CR(r); const float v = __builtin_fmaf(ssl, rel, p[r]); p[r] = (rel <= 64.f) ? v : -1e30f; tmax = fmaxf(tmax, p[r]); }
;             } else {
; #pragma unroll
;                 for (int r = 0; r < 16; ++r) { const float rel = relb + AT_CR(r); p[r] = __builtin_fmaf(ssl, rel, p[r]); tmax = fmaxf(tmax, p[r]); }
;             }
;         } else {
; #pragma unroll
;             for (int r = 0; r < 16; ++r) { const float rel = relb + AT_CR(r); const bool ok = (rel >= lo_i) && (rel <= hi_i);
;                 p[r] = ok ? p[r] - sl * fabsf(rel) : -1e30f; tmax = fmaxf(tmax, p[r]); }
.LBB0_381:
	s_cmpk_lg_i32 s15, 0x80
	s_cbranch_scc1 mk_p2a_q_skip
	s_cmp_lg_u64 s[46:47], 0
	s_cbranch_scc0 mk_p2a_q_skip
	v_mul_lo_u32 v218, s39, v173
	v_add_lshl_u32 v218, v218, s67, 8
	v_mov_b32_e32 v219, v113
	v_lshl_add_u64 v[218:219], s[12:13], 0, v[218:219]
	v_lshl_add_u64 v[218:219], v[114:115], 1, v[218:219]
	global_load_dwordx4 v[80:83], v[218:219], off
	global_load_dwordx4 v[84:87], v[218:219], off offset:32
	global_load_dwordx4 v[88:91], v[218:219], off offset:64
	global_load_dwordx4 v[92:95], v[218:219], off offset:96
	global_load_dwordx4 v[96:99], v[218:219], off offset:128
	global_load_dwordx4 v[100:103], v[218:219], off offset:160
	global_load_dwordx4 v[104:107], v[218:219], off offset:192
	global_load_dwordx4 v[108:111], v[218:219], off offset:224
mk_p2a_q_skip:
	s_waitcnt lgkmcnt(0)
	v_mfma_f32_32x32x16_fp8_fp8 v[64:79], v[64:65], v[134:135], 0
	s_cmp_lg_u32 s15, 64
	s_cselect_b64 s[8:9], -1, 0
	s_or_b64 s[8:9], s[60:61], s[8:9]
	s_and_b64 vcc, exec, s[8:9]
	v_mfma_f32_32x32x16_fp8_fp8 v[64:79], v[164:165], v[136:137], v[64:79]
	v_mfma_f32_32x32x16_fp8_fp8 v[64:79], v[162:163], v[138:139], v[64:79]
	v_mfma_f32_32x32x16_fp8_fp8 v[64:79], v[160:161], v[140:141], v[64:79]
	v_mfma_f32_32x32x16_fp8_fp8 v[64:79], v[158:159], v[142:143], v[64:79]
	v_mfma_f32_32x32x16_fp8_fp8 v[64:79], v[152:153], v[144:145], v[64:79]
	v_add_u32_e32 v152, s6, v175
	v_cvt_f32_i32_e32 v152, v152
	s_mov_b64 s[6:7], -1
	v_add_f32_e32 v158, 0xc1000000, v152
	v_add_f32_e32 v164, 0x41000000, v158
	v_mfma_f32_32x32x16_fp8_fp8 v[64:79], v[154:155], v[146:147], v[64:79]
	v_mfma_f32_32x32x16_fp8_fp8 v[64:79], v[156:157], v[148:149], v[64:79]
	s_cbranch_vccz .LBB0_392
	s_andn2_b64 vcc, exec, s[60:61]
	s_cbranch_vccnz .LBB0_384
	v_add_f32_e32 v153, 0x41100000, v158
	v_cmp_ge_f32_e32 vcc, v153, v117
	v_cmp_le_f32_e64 s[8:9], v153, v119
	v_and_b32_e32 v152, 0x7fffffff, v164
	v_and_b32_e32 v153, 0x7fffffff, v153
	v_cmp_ge_f32_e64 s[6:7], v164, v132
	v_cmp_le_f32_e64 s[10:11], v164, v130
	s_nop 1
	v_pk_fma_f32 v[152:153], v[128:129], v[152:153], v[64:65] neg_lo:[1,0,0] neg_hi:[1,0,0]
	s_and_b64 vcc, vcc, s[8:9]
	v_cndmask_b32_e32 v153, v202, v153, vcc
	s_and_b64 vcc, s[6:7], s[10:11]
	v_pk_add_f32 v[154:155], v[158:159], s[18:19] op_sel_hi:[0,1]
	v_cndmask_b32_e32 v152, v202, v152, vcc
	v_cmp_ge_f32_e32 vcc, v155, v117
	v_cmp_ge_f32_e64 s[6:7], v154, v132
	v_cmp_le_f32_e64 s[8:9], v155, v119
	v_cmp_le_f32_e64 s[10:11], v154, v130
	v_and_b32_e32 v155, 0x7fffffff, v155
	v_and_b32_e32 v154, 0x7fffffff, v154
	v_pk_fma_f32 v[154:155], v[128:129], v[154:155], v[66:67] neg_lo:[1,0,0] neg_hi:[1,0,0]
	s_and_b64 vcc, vcc, s[8:9]
	v_cndmask_b32_e32 v155, v202, v155, vcc
	s_and_b64 vcc, s[6:7], s[10:11]
	v_max3_f32 v156, v152, s89, v153
	v_cndmask_b32_e32 v154, v202, v154, vcc
	v_max3_f32 v159, v156, v154, v155
	v_pk_add_f32 v[156:157], v[158:159], s[20:21] op_sel_hi:[0,1]
	v_cmp_ge_f32_e32 vcc, v157, v117
	v_cmp_ge_f32_e64 s[6:7], v156, v132
	v_cmp_le_f32_e64 s[8:9], v157, v119
	v_cmp_le_f32_e64 s[10:11], v156, v130
	v_and_b32_e32 v157, 0x7fffffff, v157
	v_and_b32_e32 v156, 0x7fffffff, v156
	v_pk_fma_f32 v[156:157], v[128:129], v[156:157], v[68:69] neg_lo:[1,0,0] neg_hi:[1,0,0]
	s_and_b64 vcc, vcc, s[8:9]
	v_cndmask_b32_e32 v157, v202, v157, vcc
	s_and_b64 vcc, s[6:7], s[10:11]
	v_cndmask_b32_e32 v156, v202, v156, vcc
	v_max3_f32 v159, v159, v156, v157
	v_pk_add_f32 v[160:161], v[158:159], s[22:23] op_sel_hi:[0,1]
	v_cmp_ge_f32_e32 vcc, v161, v117
	v_cmp_ge_f32_e64 s[6:7], v160, v132
	v_cmp_le_f32_e64 s[8:9], v161, v119
	v_cmp_le_f32_e64 s[10:11], v160, v130
	v_and_b32_e32 v161, 0x7fffffff, v161
	v_and_b32_e32 v160, 0x7fffffff, v160
	v_pk_fma_f32 v[160:161], v[128:129], v[160:161], v[70:71] neg_lo:[1,0,0] neg_hi:[1,0,0]
	s_and_b64 vcc, vcc, s[8:9]
	v_cndmask_b32_e32 v161, v202, v161, vcc
	s_and_b64 vcc, s[6:7], s[10:11]
	v_cndmask_b32_e32 v160, v202, v160, vcc
	v_max3_f32 v159, v159, v160, v161
	v_pk_add_f32 v[162:163], v[158:159], s[24:25] op_sel_hi:[0,1]
	v_cmp_ge_f32_e32 vcc, v163, v117
	v_cmp_ge_f32_e64 s[6:7], v162, v132
	v_cmp_le_f32_e64 s[8:9], v163, v119
	v_cmp_le_f32_e64 s[10:11], v162, v130
	v_and_b32_e32 v163, 0x7fffffff, v163
	v_and_b32_e32 v162, 0x7fffffff, v162
	v_pk_fma_f32 v[162:163], v[128:129], v[162:163], v[72:73] neg_lo:[1,0,0] neg_hi:[1,0,0]
	s_and_b64 vcc, vcc, s[8:9]
	v_cndmask_b32_e32 v163, v202, v163, vcc
	s_and_b64 vcc, s[6:7], s[10:11]
	v_cndmask_b32_e32 v162, v202, v162, vcc
	v_max3_f32 v159, v159, v162, v163
	v_pk_add_f32 v[166:167], v[158:159], s[26:27] op_sel_hi:[0,1]
	v_cmp_ge_f32_e32 vcc, v167, v117
	v_cmp_ge_f32_e64 s[6:7], v166, v132
	v_cmp_le_f32_e64 s[8:9], v167, v119
	v_cmp_le_f32_e64 s[10:11], v166, v130
	v_and_b32_e32 v167, 0x7fffffff, v167
	v_and_b32_e32 v166, 0x7fffffff, v166
	v_pk_fma_f32 v[166:167], v[128:129], v[166:167], v[74:75] neg_lo:[1,0,0] neg_hi:[1,0,0]
	s_and_b64 vcc, vcc, s[8:9]
	v_cndmask_b32_e32 v167, v202, v167, vcc
	s_and_b64 vcc, s[6:7], s[10:11]
	v_cndmask_b32_e32 v166, v202, v166, vcc
	v_max3_f32 v159, v159, v166, v167
	v_pk_add_f32 v[168:169], v[158:159], s[28:29] op_sel_hi:[0,1]
	v_cmp_ge_f32_e32 vcc, v169, v117
	v_cmp_ge_f32_e64 s[6:7], v168, v132
	v_cmp_le_f32_e64 s[8:9], v169, v119
	v_cmp_le_f32_e64 s[10:11], v168, v130
	v_and_b32_e32 v169, 0x7fffffff, v169
	v_and_b32_e32 v168, 0x7fffffff, v168
	v_pk_fma_f32 v[168:169], v[128:129], v[168:169], v[76:77] neg_lo:[1,0,0] neg_hi:[1,0,0]
	s_and_b64 vcc, vcc, s[8:9]
	v_cndmask_b32_e32 v169, v202, v169, vcc
	s_and_b64 vcc, s[6:7], s[10:11]
	v_cndmask_b32_e32 v168, v202, v168, vcc
	v_max3_f32 v159, v159, v168, v169
	v_pk_add_f32 v[170:171], v[158:159], s[30:31] op_sel_hi:[0,1]
	v_cmp_ge_f32_e32 vcc, v171, v117
	v_cmp_ge_f32_e64 s[6:7], v170, v132
	v_cmp_le_f32_e64 s[8:9], v171, v119
	v_cmp_le_f32_e64 s[10:11], v170, v130
	v_and_b32_e32 v171, 0x7fffffff, v171
	v_and_b32_e32 v170, 0x7fffffff, v170
	v_pk_fma_f32 v[170:171], v[128:129], v[170:171], v[78:79] neg_lo:[1,0,0] neg_hi:[1,0,0]
	s_and_b64 vcc, vcc, s[8:9]
	v_cndmask_b32_e32 v171, v202, v171, vcc
	s_and_b64 vcc, s[6:7], s[10:11]
	v_cndmask_b32_e32 v170, v202, v170, vcc
	v_max3_f32 v159, v159, v170, v171
	s_mov_b64 s[6:7], 0

; __device__ __forceinline__ void attn_unit(const bool FINAL, const bool HN, LAS unsigned char* wl, const bf16_t* qb, const bf16_t* kb, const bf16_t* vb, int tq0, int dil, float sl, bf16x8 (&qr)[8], const bf16_t* nqb, const bf16_t* nkb, const bf16_t* nvb, int ntq0, int ndil, ...
;     ...
;         if (n < 4 || HN) asm volatile("s_waitcnt vmcnt(4)" ::: "memory");
;         else asm volatile("s_waitcnt vmcnt(0)" ::: "memory");
.LBB0_400:
	s_andn2_b64 vcc, exec, s[6:7]
	s_cbranch_vccnz .LBB0_402
	s_cmpk_eq_i32 s15, 0x80
	s_cbranch_scc1 mk_p2a_w12
	s_waitcnt vmcnt(4)
	s_branch .LBB0_402
mk_p2a_w12:
	s_waitcnt vmcnt(12)

; #define GAS __attribute__((address_space(1)))
; __device__ __forceinline__ void attn_unit(const bool FINAL, const bool HN, LAS unsigned char* wl, const bf16_t* qb, const bf16_t* kb, const bf16_t* vb, int tq0, int dil, float sl, bf16x8 (&qr)[8], const bf16_t* nqb, const bf16_t* nkb, const bf16_t* nvb, int ntq0, int ndil, ...
;     ...
;     if (HN) at_load_q(qr, nqb, ntq0, ndil, lane);
;     const int tq = tq0 + dil * r32;
;     v4u a0[8], a1v[8];
;     if (FINAL) {
; #pragma unroll
;         for (int i = 0; i < 8; ++i) { const int row = 4 * i + rr0, c = cs ^ (row & 15); const size_t off = (size_t)(tq0 + dil * row) * 128 + 8 * c;
;             a0[i] = __builtin_nontemporal_load((const GAS v4u*)(part0 + off)); a1v[i] = __builtin_nontemporal_load((const GAS v4u*)(part1 + off)); } }
;     float osc, c1 = 0.f, c2 = 0.f;
;     if (!FINAL) { osc = 1.0f / l_run; if (hi == 0) *(GAS f32x2*)(ml + (size_t)tq * 2) = (f32x2){m_run, l_run}; }
.LBB0_410:
	s_and_b64 vcc, exec, s[46:47]
	s_cbranch_vccz .LBB0_412
.LBB0_412:
	s_and_saveexec_b64 s[6:7], s[4:5]
	s_cbranch_execz .LBB0_414
	v_mul_lo_u32 v66, s88, v131
	v_add_lshl_u32 v66, v66, s92, 1
	v_mov_b32_e32 v67, v113
	v_lshl_add_u64 v[66:67], v[66:67], 2, s[44:45]
	global_store_dwordx2 v[66:67], v[64:65], off
